# c17_delta32
# baseline (speedup 1.0000x reference)
.LBB0_1430:
	v_max_f32_e32 v2, v129, v129
	v_max_f32_e32 v129, v128, v128
	v_max_f32_e32 v2, v129, v2
	v_max3_f32 v2, v2, v130, v131
	v_max3_f32 v2, v2, v132, v133
	v_max3_f32 v2, v2, v134, v135
	v_max3_f32 v2, v2, v136, v137
	v_max3_f32 v2, v2, v138, v139
	v_max3_f32 v2, v2, v140, v141
	v_max3_f32 v2, v2, v142, v197
	v_max3_f32 v2, v2, v112, v113
	v_max3_f32 v2, v2, v114, v115
	v_max3_f32 v2, v2, v116, v117
	v_max3_f32 v2, v2, v118, v119
	v_max3_f32 v2, v2, v120, v121
	v_max3_f32 v2, v2, v122, v123
	v_max3_f32 v2, v2, v124, v125
	v_max3_f32 v2, v2, v126, v127
	v_mov_b32_e32 v113, v2
	s_nop 1
	v_permlane32_swap_b32_e32 v2, v113
	v_max_f32_e32 v113, v113, v113
	v_max_f32_e32 v2, v2, v2
	v_max_f32_e32 v2, v2, v113
	v_cmp_ge_f32_e32 vcc, s68, v2
	s_cmp_eq_u64 vcc, exec
	v_mov_b32_e32 v225, 1.0
	s_cbranch_scc1 .LBB0_1432
	v_max_f32_e32 v2, v2, v2
	v_add_f32_e32 v245, 0x42000000, v2
	v_min_f32_e32 v245, 0x42f00000, v245
	v_max3_f32 v2, v245, v2, 0
	v_mov_b32_e32 v112, v80
	v_exp_f32_e64 v225, -v2
	v_mov_b32_e32 v80, v81
	v_mov_b32_e32 v81, v82
	v_mov_b32_e32 v82, v83
	v_mov_b32_e32 v83, v84
	v_mov_b32_e32 v84, v85
	v_mov_b32_e32 v85, v86
	v_mov_b32_e32 v86, v87
	v_mov_b32_e32 v87, v88
	v_mov_b32_e32 v88, v89
	v_mov_b32_e32 v89, v90
	v_mov_b32_e32 v90, v91
	v_mov_b32_e32 v91, v92
	v_mov_b32_e32 v113, v96
	v_mov_b32_e32 v96, v97
	v_mov_b32_e32 v97, v98
	v_pk_add_f32 v[116:117], v[80:81], v[2:3] op_sel_hi:[1,0] neg_lo:[0,1] neg_hi:[0,1]
	v_mov_b32_e32 v80, v99
	v_mov_b32_e32 v81, v100
	v_pk_add_f32 v[118:119], v[82:83], v[2:3] op_sel_hi:[1,0] neg_lo:[0,1] neg_hi:[0,1]
	v_mov_b32_e32 v82, v101
	v_mov_b32_e32 v83, v102
	v_pk_add_f32 v[120:121], v[84:85], v[2:3] op_sel_hi:[1,0] neg_lo:[0,1] neg_hi:[0,1]
	v_mov_b32_e32 v84, v103
	v_mov_b32_e32 v85, v104
	v_pk_add_f32 v[122:123], v[86:87], v[2:3] op_sel_hi:[1,0] neg_lo:[0,1] neg_hi:[0,1]
	v_mov_b32_e32 v86, v105
	v_mov_b32_e32 v87, v106
	v_pk_add_f32 v[124:125], v[88:89], v[2:3] op_sel_hi:[1,0] neg_lo:[0,1] neg_hi:[0,1]
	v_mov_b32_e32 v88, v107
	v_mov_b32_e32 v89, v108
	v_pk_add_f32 v[128:129], v[90:91], v[2:3] op_sel_hi:[1,0] neg_lo:[0,1] neg_hi:[0,1]
	v_mov_b32_e32 v90, v109
	v_mov_b32_e32 v91, v110
	v_mov_b32_e32 v92, v93
	v_mov_b32_e32 v93, v94
	v_pk_add_f32 v[112:113], v[112:113], v[2:3] op_sel_hi:[1,0] neg_lo:[0,1] neg_hi:[0,1]
	v_pk_add_f32 v[114:115], v[96:97], v[2:3] op_sel_hi:[1,0] neg_lo:[0,1] neg_hi:[0,1]
	v_pk_add_f32 v[80:81], v[80:81], v[2:3] op_sel_hi:[1,0] neg_lo:[0,1] neg_hi:[0,1]
	v_pk_add_f32 v[82:83], v[82:83], v[2:3] op_sel_hi:[1,0] neg_lo:[0,1] neg_hi:[0,1]
	v_pk_add_f32 v[84:85], v[84:85], v[2:3] op_sel_hi:[1,0] neg_lo:[0,1] neg_hi:[0,1]
	v_pk_add_f32 v[86:87], v[86:87], v[2:3] op_sel_hi:[1,0] neg_lo:[0,1] neg_hi:[0,1]
	v_pk_add_f32 v[88:89], v[88:89], v[2:3] op_sel_hi:[1,0] neg_lo:[0,1] neg_hi:[0,1]
	v_pk_add_f32 v[90:91], v[90:91], v[2:3] op_sel_hi:[1,0] neg_lo:[0,1] neg_hi:[0,1]
	v_pk_add_f32 v[130:131], v[92:93], v[2:3] op_sel_hi:[1,0] neg_lo:[0,1] neg_hi:[0,1]
	v_add_f32_e32 v221, v221, v2
	v_sub_f32_e32 v111, v197, v2
	v_sub_f32_e32 v95, v127, v2
	v_mov_b32_e32 v97, v114
	v_mov_b32_e32 v98, v115
	v_mov_b32_e32 v99, v80
	v_mov_b32_e32 v100, v81
	v_mov_b32_e32 v101, v82
	v_mov_b32_e32 v102, v83
	v_mov_b32_e32 v103, v84
	v_mov_b32_e32 v104, v85
	v_mov_b32_e32 v105, v86
	v_mov_b32_e32 v106, v87
	v_mov_b32_e32 v107, v88
	v_mov_b32_e32 v108, v89
	v_mov_b32_e32 v109, v90
	v_mov_b32_e32 v110, v91
	v_mov_b32_e32 v81, v116
	v_mov_b32_e32 v82, v117
	v_mov_b32_e32 v83, v118
	v_mov_b32_e32 v84, v119
	v_mov_b32_e32 v85, v120
	v_mov_b32_e32 v86, v121
	v_mov_b32_e32 v87, v122
	v_mov_b32_e32 v88, v123
	v_mov_b32_e32 v89, v124
	v_mov_b32_e32 v90, v125
	v_mov_b32_e32 v91, v128
	v_mov_b32_e32 v92, v129
	v_mov_b32_e32 v93, v130
	v_mov_b32_e32 v94, v131
	v_mov_b32_e32 v128, v113
	s_branch .LBB0_1433

.Lf_odd_resc:
	v_add_f32_e32 v246, 0x42000000, v245
	v_min_f32_e32 v246, 0x42f00000, v246
	v_max3_f32 v245, v246, v245, 0
	v_exp_f32_e64 v225, -v245
	v_add_f32_e32 v221, v221, v245
	v_sub_f32_e32 v128, v128, v245
	v_sub_f32_e32 v129, v129, v245
	v_sub_f32_e32 v130, v130, v245
	v_sub_f32_e32 v131, v131, v245
	v_sub_f32_e32 v132, v132, v245
	v_sub_f32_e32 v133, v133, v245
	v_sub_f32_e32 v134, v134, v245
	v_sub_f32_e32 v135, v135, v245
	v_sub_f32_e32 v136, v136, v245
	v_sub_f32_e32 v137, v137, v245
	v_sub_f32_e32 v138, v138, v245
	v_sub_f32_e32 v139, v139, v245
	v_sub_f32_e32 v140, v140, v245
	v_sub_f32_e32 v141, v141, v245
	v_sub_f32_e32 v142, v142, v245
	v_sub_f32_e32 v143, v143, v245
	v_sub_f32_e32 v112, v112, v245
	v_sub_f32_e32 v113, v113, v245
	v_sub_f32_e32 v114, v114, v245
	v_sub_f32_e32 v115, v115, v245
	v_sub_f32_e32 v116, v116, v245
	v_sub_f32_e32 v117, v117, v245
	v_sub_f32_e32 v118, v118, v245
	v_sub_f32_e32 v119, v119, v245
	v_sub_f32_e32 v120, v120, v245
	v_sub_f32_e32 v121, v121, v245
	v_sub_f32_e32 v122, v122, v245
	v_sub_f32_e32 v123, v123, v245
	v_sub_f32_e32 v124, v124, v245
	v_sub_f32_e32 v125, v125, v245
	v_sub_f32_e32 v126, v126, v245
	v_sub_f32_e32 v127, v127, v245
	s_branch .Lf_odd_exp

.LBB0_1445:
	v_max_f32_e32 v129, v129, v129
	v_max_f32_e32 v143, v128, v128
	v_max_f32_e32 v129, v143, v129
	v_max3_f32 v129, v129, v130, v131
	v_max3_f32 v129, v129, v132, v133
	v_max3_f32 v129, v129, v134, v135
	v_max3_f32 v129, v129, v136, v137
	v_max3_f32 v129, v129, v138, v139
	v_max3_f32 v129, v129, v140, v141
	v_max3_f32 v129, v129, v142, v197
	v_max3_f32 v113, v129, v112, v113
	v_max3_f32 v113, v113, v114, v115
	v_max3_f32 v113, v113, v116, v117
	v_max3_f32 v113, v113, v118, v119
	v_max3_f32 v113, v113, v120, v121
	v_max3_f32 v113, v113, v122, v123
	v_max3_f32 v113, v113, v124, v125
	v_max3_f32 v113, v113, v126, v127
	v_mov_b32_e32 v114, v113
	s_nop 1
	v_permlane32_swap_b32_e32 v113, v114
	v_max_f32_e32 v114, v114, v114
	v_max_f32_e32 v113, v113, v113
	v_max_f32_e32 v113, v113, v114
	v_cmp_ge_f32_e32 vcc, s68, v113
	s_cmp_eq_u64 vcc, exec
	v_mov_b32_e32 v196, 1.0
	s_cbranch_scc1 .LBB0_1447
	v_mov_b32_e32 v114, v80
	v_max_f32_e32 v80, v113, v113
	v_mov_b32_e32 v115, v96
	v_add_f32_e32 v245, 0x42000000, v80
	v_min_f32_e32 v245, 0x42f00000, v245
	v_max3_f32 v80, v245, v80, 0
	v_mov_b32_e32 v96, v97
	v_mov_b32_e32 v97, v98
	v_exp_f32_e64 v196, -v80
	v_pk_add_f32 v[112:113], v[114:115], v[80:81] op_sel_hi:[1,0] neg_lo:[0,1] neg_hi:[0,1]
	v_pk_add_f32 v[114:115], v[96:97], v[80:81] op_sel_hi:[1,0] neg_lo:[0,1] neg_hi:[0,1]
	v_mov_b32_e32 v96, v81
	v_mov_b32_e32 v97, v82
	v_mov_b32_e32 v82, v83
	v_mov_b32_e32 v83, v84
	v_mov_b32_e32 v84, v85
	v_mov_b32_e32 v85, v86
	v_mov_b32_e32 v86, v87
	v_mov_b32_e32 v87, v88
	v_mov_b32_e32 v88, v89
	v_mov_b32_e32 v89, v90
	v_mov_b32_e32 v90, v91
	v_mov_b32_e32 v91, v92
	v_pk_add_f32 v[116:117], v[96:97], v[80:81] op_sel_hi:[1,0] neg_lo:[0,1] neg_hi:[0,1]
	v_mov_b32_e32 v96, v99
	v_mov_b32_e32 v97, v100
	v_pk_add_f32 v[120:121], v[82:83], v[80:81] op_sel_hi:[1,0] neg_lo:[0,1] neg_hi:[0,1]
	v_mov_b32_e32 v82, v101
	v_mov_b32_e32 v83, v102
	v_pk_add_f32 v[122:123], v[84:85], v[80:81] op_sel_hi:[1,0] neg_lo:[0,1] neg_hi:[0,1]
	v_mov_b32_e32 v84, v103
	v_mov_b32_e32 v85, v104
	v_pk_add_f32 v[124:125], v[86:87], v[80:81] op_sel_hi:[1,0] neg_lo:[0,1] neg_hi:[0,1]
	v_mov_b32_e32 v86, v105
	v_mov_b32_e32 v87, v106
	v_pk_add_f32 v[128:129], v[88:89], v[80:81] op_sel_hi:[1,0] neg_lo:[0,1] neg_hi:[0,1]
	v_mov_b32_e32 v88, v107
	v_mov_b32_e32 v89, v108
	v_pk_add_f32 v[130:131], v[90:91], v[80:81] op_sel_hi:[1,0] neg_lo:[0,1] neg_hi:[0,1]
	v_mov_b32_e32 v90, v109
	v_mov_b32_e32 v91, v110
	v_mov_b32_e32 v92, v93
	v_mov_b32_e32 v93, v94
	v_pk_add_f32 v[118:119], v[96:97], v[80:81] op_sel_hi:[1,0] neg_lo:[0,1] neg_hi:[0,1]
	v_pk_add_f32 v[82:83], v[82:83], v[80:81] op_sel_hi:[1,0] neg_lo:[0,1] neg_hi:[0,1]
	v_pk_add_f32 v[84:85], v[84:85], v[80:81] op_sel_hi:[1,0] neg_lo:[0,1] neg_hi:[0,1]
	v_pk_add_f32 v[86:87], v[86:87], v[80:81] op_sel_hi:[1,0] neg_lo:[0,1] neg_hi:[0,1]
	v_pk_add_f32 v[88:89], v[88:89], v[80:81] op_sel_hi:[1,0] neg_lo:[0,1] neg_hi:[0,1]
	v_pk_add_f32 v[90:91], v[90:91], v[80:81] op_sel_hi:[1,0] neg_lo:[0,1] neg_hi:[0,1]
	v_pk_add_f32 v[132:133], v[92:93], v[80:81] op_sel_hi:[1,0] neg_lo:[0,1] neg_hi:[0,1]
	v_add_f32_e32 v221, v221, v80
	v_sub_f32_e32 v111, v197, v80
	v_sub_f32_e32 v95, v127, v80
	v_mov_b32_e32 v97, v114
	v_mov_b32_e32 v98, v115
	v_mov_b32_e32 v99, v118
	v_mov_b32_e32 v100, v119
	v_mov_b32_e32 v101, v82
	v_mov_b32_e32 v102, v83
	v_mov_b32_e32 v103, v84
	v_mov_b32_e32 v104, v85
	v_mov_b32_e32 v105, v86
	v_mov_b32_e32 v106, v87
	v_mov_b32_e32 v107, v88
	v_mov_b32_e32 v108, v89
	v_mov_b32_e32 v109, v90
	v_mov_b32_e32 v110, v91
	v_mov_b32_e32 v81, v116
	v_mov_b32_e32 v82, v117
	v_mov_b32_e32 v83, v120
	v_mov_b32_e32 v84, v121
	v_mov_b32_e32 v85, v122
	v_mov_b32_e32 v86, v123
	v_mov_b32_e32 v87, v124
	v_mov_b32_e32 v88, v125
	v_mov_b32_e32 v89, v128
	v_mov_b32_e32 v90, v129
	v_mov_b32_e32 v91, v130
	v_mov_b32_e32 v92, v131
	v_mov_b32_e32 v93, v132
	v_mov_b32_e32 v94, v133
	v_mov_b32_e32 v128, v113
	s_branch .LBB0_1448

.Lf_even_resc:
	v_add_f32_e32 v246, 0x42000000, v245
	v_min_f32_e32 v246, 0x42f00000, v246
	v_max3_f32 v245, v246, v245, 0
	v_exp_f32_e64 v196, -v245
	v_add_f32_e32 v221, v221, v245
	v_sub_f32_e32 v128, v128, v245
	v_sub_f32_e32 v129, v129, v245
	v_sub_f32_e32 v130, v130, v245
	v_sub_f32_e32 v131, v131, v245
	v_sub_f32_e32 v132, v132, v245
	v_sub_f32_e32 v133, v133, v245
	v_sub_f32_e32 v134, v134, v245
	v_sub_f32_e32 v135, v135, v245
	v_sub_f32_e32 v136, v136, v245
	v_sub_f32_e32 v137, v137, v245
	v_sub_f32_e32 v138, v138, v245
	v_sub_f32_e32 v139, v139, v245
	v_sub_f32_e32 v140, v140, v245
	v_sub_f32_e32 v141, v141, v245
	v_sub_f32_e32 v142, v142, v245
	v_sub_f32_e32 v143, v143, v245
	v_sub_f32_e32 v112, v112, v245
	v_sub_f32_e32 v113, v113, v245
	v_sub_f32_e32 v114, v114, v245
	v_sub_f32_e32 v115, v115, v245
	v_sub_f32_e32 v116, v116, v245
	v_sub_f32_e32 v117, v117, v245
	v_sub_f32_e32 v118, v118, v245
	v_sub_f32_e32 v119, v119, v245
	v_sub_f32_e32 v120, v120, v245
	v_sub_f32_e32 v121, v121, v245
	v_sub_f32_e32 v122, v122, v245
	v_sub_f32_e32 v123, v123, v245
	v_sub_f32_e32 v124, v124, v245
	v_sub_f32_e32 v125, v125, v245
	v_sub_f32_e32 v126, v126, v245
	v_sub_f32_e32 v127, v127, v245
	s_branch .Lf_even_exp
